# HGRN in-proj GEMM: 64 sixth-round heavy (forget-gate epilogue) tiles exchanged with light tiles of five-tile workgroups; no WG has 6 tiles and 3 heavy epilogues
# speedup vs baseline: 1.0036x; 1.0036x over previous
; #define G_STAGE(bufoff, gbase, voff) do { _Pragma("unroll") for (int _i = 0; _i < 2; ++_i) \
;         __builtin_amdgcn_global_load_lds((const unsigned*)((const char*)(gbase) + voff[_i]), (LAS unsigned*)(lds + (bufoff) + ldsw + _i * 8192), 16, 0, 0); } while (0)
; template <class Get, class Epi>
; DI void gemm_loop(int ntiles, int ld, char* shm, const Get& get, const Epi& epi) {
;     ...
;     for (int i = 0; i < 2; ++i) { int R, C; stage_rc(tid * 16 + i * 8192, R, C); const int rho = R & 31, Rb = (R & ~31) + 8 * ((rho & 15) >> 2) + 4 * (rho >> 4) + (rho & 3);
;         voffA[i] = (unsigned)(R * ld + C) * 2u; voffB[i] = (unsigned)(Rb * ld + C) * 2u; }
;     const size_t kstep = (size_t)(BK * 2), hstep = (size_t)HALF * ld * 2;
;     const unsigned ldsw = (unsigned)wid * 1024u;
;     const int aoff = lds_byte(wr * 64 + fr, fq * 8), boff = lds_byte(wc * 32 + fr, fq * 8);
;     ...
;     int L = bx; if (L >= ntiles) return;
;     Tile cur = get(L), nxt = cur;
;     AccT acc;
;     ...
;     G_ZERO;
;     bf16x8 At[4][2], B0[2][2], B1[2][2];
;     const char* cA = (const char*)cur.A + (size_t)cur.brow * ld * 2; const char* cB = (const char*)cur.Bt + (size_t)cur.bcol * ld * 2;
;     G_STAGE(G_SB(0, 0), cB, voffB); G_STAGE(G_SB(0, 1), cB + hstep, voffB); G_STAGE(G_SA(0, 0), cA, voffA); G_STAGE(G_SA(0, 1), cA + hstep, voffA);
.LBB0_2013:
	s_or_b64 exec, exec, s[0:1]
	s_add_u32 s34, s68, 0x16ade000
	s_addc_u32 s35, s69, 0
	v_mov_b32_e32 v9, v252
	s_mov_b32 s52, s87
	s_waitcnt lgkmcnt(0)
	s_barrier
	s_cmpk_gt_i32 s52, 0x59f
	v_readfirstlane_b32 s14, v9
	s_cbranch_scc1 .LBB0_2357
	v_lshlrev_b32_e32 v0, 4, v9
	v_add_u32_e32 v1, 0x2000, v0
	v_ashrrev_i32_e32 v2, 31, v1
	v_lshrrev_b32_e32 v2, 22, v2
	v_add_u32_e32 v2, v1, v2
	v_ashrrev_i32_e32 v8, 10, v2
	v_mul_i32_i24_e32 v2, 0x400, v8
	v_sub_u32_e32 v1, v1, v2
	v_lshrrev_b32_e32 v2, 4, v1
	v_bitop3_b32 v1, v2, v1, 32 bitop3:0x6c
	v_ashrrev_i32_e32 v2, 31, v1
	v_lshrrev_b32_e32 v2, 26, v2
	v_add_u32_e32 v2, v1, v2
	v_lshlrev_b32_e32 v3, 3, v8
	v_ashrrev_i32_e32 v10, 6, v2
	v_and_b32_e32 v3, -16, v3
	v_add_u32_e32 v3, v10, v3
	v_and_b32_e32 v4, 3, v10
	s_mov_b32 s0, 0x1fffe0
	v_lshlrev_b32_e32 v5, 1, v3
	v_lshrrev_b32_e32 v6, 2, v3
	v_and_b32_e32 v2, 0xc0, v2
	v_and_or_b32 v4, v3, s0, v4
	v_and_b32_e32 v5, 24, v5
	v_and_b32_e32 v6, 4, v6
	v_sub_u32_e32 v1, v1, v2
	v_mov_b32_e32 v2, 1
	v_or3_b32 v4, v4, v5, v6
	v_lshlrev_b32_e32 v5, 5, v8
	v_ashrrev_i16_sdwa v1, v2, sext(v1) dst_sel:DWORD dst_unused:UNUSED_PAD src0_sel:DWORD src1_sel:BYTE_0
	v_and_b32_e32 v5, 32, v5
	v_bfe_i32 v11, v1, 0, 16
	v_add_lshl_u32 v1, v5, v11, 1
	v_lshl_add_u32 v136, v4, 11, v1
	v_lshl_add_u32 v138, v3, 11, v1
	v_bfe_i32 v1, v9, 27, 1
	v_lshrrev_b32_e32 v1, 22, v1
	v_add_u32_e32 v1, v0, v1
	v_and_b32_e32 v1, 0xfffffc00, v1
	v_sub_u32_e32 v0, v0, v1
	v_lshrrev_b32_e32 v1, 4, v0
	v_ashrrev_i32_e32 v3, 31, v9
	v_bitop3_b32 v0, v1, v0, 32 bitop3:0x6c
	v_lshrrev_b32_e32 v3, 26, v3
	v_ashrrev_i32_e32 v1, 31, v0
	v_add_u32_e32 v3, v9, v3
	v_lshrrev_b32_e32 v1, 26, v1
	v_ashrrev_i32_e32 v13, 6, v3
	v_add_u32_e32 v1, v0, v1
	v_lshlrev_b32_e32 v3, 3, v13
	v_ashrrev_i32_e32 v12, 6, v1
	v_and_b32_e32 v3, -16, v3
	v_add_u32_e32 v3, v12, v3
	v_and_b32_e32 v4, 3, v12
	v_and_or_b32 v4, v3, s0, v4
	s_mov_b32 s98, 0
	s_add_i32 s99, s52, 0xfffffaa0
	s_cmp_lt_u32 s99, 0x40
	s_cselect_b32 s1, 0xfffffd40, 0
	s_and_b32 s99, s52, 7
	s_add_i32 s99, s99, 0xffffffff
	s_cmp_lt_u32 s99, 1
	s_cselect_b32 s1, s1, 0
	s_add_i32 s98, s98, s1
	s_add_i32 s99, s52, 0xfffffb00
	s_cmp_lt_u32 s99, 0x60
	s_cselect_b32 s1, 0xfffffda0, 0
	s_and_b32 s99, s52, 7
	s_add_i32 s99, s99, 0xfffffffe
	s_cmp_lt_u32 s99, 3
	s_cselect_b32 s1, s1, 0
	s_add_i32 s98, s98, s1
	s_add_i32 s99, s52, 0xfffffaa0
	s_cmp_lt_u32 s99, 0x40
	s_cselect_b32 s1, 0xfffffb3e, 0
	s_and_b32 s99, s52, 7
	s_add_i32 s99, s99, 0xfffffffe
	s_cmp_lt_u32 s99, 1
	s_cselect_b32 s1, s1, 0
	s_add_i32 s98, s98, s1
	s_add_i32 s99, s52, 0xfffffaa0
	s_cmp_lt_u32 s99, 0x40
	s_cselect_b32 s1, 0xfffffb44, 0
	s_and_b32 s99, s52, 7
	s_add_i32 s99, s99, 0xfffffffd
	s_cmp_lt_u32 s99, 1
	s_cselect_b32 s1, s1, 0
	s_add_i32 s98, s98, s1
	s_add_i32 s99, s52, 0xfffffaa0
	s_cmp_lt_u32 s99, 0x20
	s_cselect_b32 s1, 0xfffffb41, 0
	s_and_b32 s99, s52, 7
	s_add_i32 s99, s99, 0xfffffffc
	s_cmp_lt_u32 s99, 1
	s_cselect_b32 s1, s1, 0
	s_add_i32 s98, s98, s1
	s_add_i32 s99, s52, 0xfffffd60
	s_cmp_lt_u32 s99, 0x40
	s_cselect_b32 s1, 0x2c0, 0
	s_and_b32 s99, s52, 7
	s_add_i32 s99, s99, 0xffffffff
	s_cmp_lt_u32 s99, 1
	s_cselect_b32 s1, s1, 0
	s_add_i32 s98, s98, s1
	s_add_i32 s99, s52, 0xfffffd60
	s_cmp_lt_u32 s99, 0x60
	s_cselect_b32 s1, 0x260, 0
	s_and_b32 s99, s52, 7
	s_add_i32 s99, s99, 0xfffffffe
	s_cmp_lt_u32 s99, 3
	s_cselect_b32 s1, s1, 0
	s_add_i32 s98, s98, s1
	s_add_i32 s99, s52, 0xffffff60
	s_cmp_lt_u32 s99, 0x40
	s_cselect_b32 s1, 0x4c2, 0
	s_and_b32 s99, s52, 7
	s_add_i32 s99, s99, 0x0
	s_cmp_lt_u32 s99, 1
	s_cselect_b32 s1, s1, 0
	s_add_i32 s98, s98, s1
	s_add_i32 s99, s52, 0xffffff60
	s_cmp_lt_u32 s99, 0x40
	s_cselect_b32 s1, 0x4bc, 0
	s_and_b32 s99, s52, 7
	s_add_i32 s99, s99, 0xfffffff9
	s_cmp_lt_u32 s99, 1
	s_cselect_b32 s1, s1, 0
	s_add_i32 s98, s98, s1
	s_add_i32 s99, s52, 0xffffff60
	s_cmp_lt_u32 s99, 0x20
	s_cselect_b32 s1, 0x4bf, 0
	s_and_b32 s99, s52, 7
	s_add_i32 s99, s99, 0xfffffffb
	s_cmp_lt_u32 s99, 1
	s_cselect_b32 s1, s1, 0
	s_add_i32 s98, s98, s1
	s_add_i32 s98, s98, s52
	s_ashr_i32 s0, s98, 31
	s_lshr_b32 s0, s0, 29
	s_add_i32 s0, s98, s0
	s_ashr_i32 s10, s14, 6
	s_ashr_i32 s1, s0, 3
	s_and_b32 s0, s0, -8
	s_ashr_i32 s11, s14, 8
	s_lshl_b32 s46, s10, 10
	s_sub_i32 s0, s98, s0
	s_cmp_lt_i32 s0, 0
	s_movk_i32 s47, 0xb5
	s_cselect_b32 s2, s47, 0xb4
	s_mul_i32 s0, s2, s0
	s_add_i32 s0, s0, s1
	s_mul_hi_i32 s1, s0, 0x66666667
	s_lshr_b32 s2, s1, 31
	s_ashr_i32 s1, s1, 6
	s_add_i32 s1, s1, s2
	s_mul_i32 s2, s1, 0xa0
	s_sub_i32 s0, s0, s2
	s_bfe_u32 s2, s0, 0x3001c
	s_add_i32 s2, s0, s2
	s_sext_i32_i16 s3, s2
	s_and_b32 s2, s2, 0xfff8
	s_sub_i32 s0, s0, s2
	s_sext_i32_i16 s0, s0
	s_lshl_b32 s1, s1, 11
	s_lshl_b32 s0, s0, 8
	s_add_i32 s0, s0, s1
	s_lshl_b32 s1, s3, 5
	v_lshlrev_b32_e32 v5, 1, v3
	v_lshrrev_b32_e32 v6, 2, v3
	v_and_b32_e32 v1, 0xc0, v1
	s_and_b32 s2, s1, 0xffffff00
	v_and_b32_e32 v5, 24, v5
	v_and_b32_e32 v6, 4, v6
	v_sub_u32_e32 v0, v0, v1
	s_ashr_i32 s1, s0, 31
	s_ashr_i32 s3, s2, 31
	v_or3_b32 v4, v4, v5, v6
	v_lshlrev_b32_e32 v5, 5, v13
	v_ashrrev_i16_sdwa v0, v2, sext(v0) dst_sel:DWORD dst_unused:UNUSED_PAD src0_sel:DWORD src1_sel:BYTE_0
	s_lshl_b64 s[4:5], s[0:1], 11
	s_lshl_b64 s[6:7], s[2:3], 11
	v_and_b32_e32 v5, 32, v5
	v_bfe_i32 v14, v0, 0, 16
	s_add_u32 s6, s22, s6
	v_add_lshl_u32 v0, v5, v14, 1
	s_addc_u32 s7, s23, s7
	s_add_i32 s50, s46, 0
	v_lshl_add_u32 v140, v4, 11, v0
	s_add_i32 m0, s50, 0x10000
	v_lshl_add_u32 v142, v3, 11, v0
	global_load_lds_dwordx4 v140, s[6:7]
	s_add_i32 m0, s50, 0x12000
	s_add_u32 s8, s6, 0x40000
	global_load_lds_dwordx4 v136, s[6:7]
	s_addc_u32 s9, s7, 0
	s_add_i32 m0, s50, 0x14000
	v_mov_b32_e32 v145, 0
	global_load_lds_dwordx4 v140, s[8:9]
	s_add_i32 m0, s50, 0x16000
	s_add_u32 s4, s16, s4
	s_addc_u32 s5, s17, s5
	s_add_i32 s51, s50, 0x2000
	global_load_lds_dwordx4 v136, s[8:9]
	s_mov_b32 m0, s50
	s_add_u32 s8, s4, 0x40000
	global_load_lds_dwordx4 v142, s[4:5]
	s_mov_b32 m0, s51
	s_addc_u32 s9, s5, 0
	s_add_i32 s71, s50, 0x4000
	global_load_lds_dwordx4 v138, s[4:5]
	s_mov_b32 m0, s71
	s_add_i32 s72, s50, 0x6000
	global_load_lds_dwordx4 v142, s[8:9]
	s_mov_b32 m0, s72
	v_mov_b32_e32 v141, v145
	global_load_lds_dwordx4 v138, s[8:9]
	v_mov_b32_e32 v137, v145
	v_mov_b32_e32 v143, v145
	v_mov_b32_e32 v139, v145
	s_cmp_eq_u32 s11, 1
	s_mov_b32 s1, 0
	v_lshl_add_u64 v[6:7], s[6:7], 0, v[140:141]
	v_lshl_add_u64 v[4:5], s[6:7], 0, v[136:137]
	v_lshl_add_u64 v[0:1], s[4:5], 0, v[142:143]
	s_cselect_b64 s[8:9], -1, 0
	s_cmp_lg_u32 s11, 1
	v_lshl_add_u64 v[2:3], s[4:5], 0, v[138:139]
	s_cbranch_scc1 .LBB0_2016
	s_barrier

; template <class Get, class Epi>
; DI void gemm_loop(int ntiles, int ld, char* shm, const Get& get, const Epi& epi) {
;     ...
;         const int Ln = L + gridDim.x; const bool has_next = Ln < ntiles; if (has_next) nxt = get(Ln);
;         const char* nA = has_next ? (const char*)nxt.A + (size_t)nxt.brow * ld * 2 : cA; const char* nB = has_next ? (const char*)nxt.Bt + (size_t)nxt.bcol * ld * 2 : cB;
.LBB0_2019:
	s_add_i32 s82, s52, s26
	s_cmpk_lt_i32 s82, 0x5a0
	s_cselect_b64 s[38:39], -1, 0
	s_cmpk_gt_i32 s82, 0x59f
	s_mov_b32 s40, s0
	s_mov_b32 s42, s2
	s_cbranch_scc1 .LBB0_2021
	s_mov_b32 s98, 0
	s_add_i32 s99, s82, 0xfffffaa0
	s_cmp_lt_u32 s99, 0x40
	s_cselect_b32 s14, 0xfffffd40, 0
	s_and_b32 s99, s82, 7
	s_add_i32 s99, s99, 0xffffffff
	s_cmp_lt_u32 s99, 1
	s_cselect_b32 s14, s14, 0
	s_add_i32 s98, s98, s14
	s_add_i32 s99, s82, 0xfffffb00
	s_cmp_lt_u32 s99, 0x60
	s_cselect_b32 s14, 0xfffffda0, 0
	s_and_b32 s99, s82, 7
	s_add_i32 s99, s99, 0xfffffffe
	s_cmp_lt_u32 s99, 3
	s_cselect_b32 s14, s14, 0
	s_add_i32 s98, s98, s14
	s_add_i32 s99, s82, 0xfffffaa0
	s_cmp_lt_u32 s99, 0x40
	s_cselect_b32 s14, 0xfffffb3e, 0
	s_and_b32 s99, s82, 7
	s_add_i32 s99, s99, 0xfffffffe
	s_cmp_lt_u32 s99, 1
	s_cselect_b32 s14, s14, 0
	s_add_i32 s98, s98, s14
	s_add_i32 s99, s82, 0xfffffaa0
	s_cmp_lt_u32 s99, 0x40
	s_cselect_b32 s14, 0xfffffb44, 0
	s_and_b32 s99, s82, 7
	s_add_i32 s99, s99, 0xfffffffd
	s_cmp_lt_u32 s99, 1
	s_cselect_b32 s14, s14, 0
	s_add_i32 s98, s98, s14
	s_add_i32 s99, s82, 0xfffffaa0
	s_cmp_lt_u32 s99, 0x20
	s_cselect_b32 s14, 0xfffffb41, 0
	s_and_b32 s99, s82, 7
	s_add_i32 s99, s99, 0xfffffffc
	s_cmp_lt_u32 s99, 1
	s_cselect_b32 s14, s14, 0
	s_add_i32 s98, s98, s14
	s_add_i32 s99, s82, 0xfffffd60
	s_cmp_lt_u32 s99, 0x40
	s_cselect_b32 s14, 0x2c0, 0
	s_and_b32 s99, s82, 7
	s_add_i32 s99, s99, 0xffffffff
	s_cmp_lt_u32 s99, 1
	s_cselect_b32 s14, s14, 0
	s_add_i32 s98, s98, s14
	s_add_i32 s99, s82, 0xfffffd60
	s_cmp_lt_u32 s99, 0x60
	s_cselect_b32 s14, 0x260, 0
	s_and_b32 s99, s82, 7
	s_add_i32 s99, s99, 0xfffffffe
	s_cmp_lt_u32 s99, 3
	s_cselect_b32 s14, s14, 0
	s_add_i32 s98, s98, s14
	s_add_i32 s99, s82, 0xffffff60
	s_cmp_lt_u32 s99, 0x40
	s_cselect_b32 s14, 0x4c2, 0
	s_and_b32 s99, s82, 7
	s_add_i32 s99, s99, 0x0
	s_cmp_lt_u32 s99, 1
	s_cselect_b32 s14, s14, 0
	s_add_i32 s98, s98, s14
	s_add_i32 s99, s82, 0xffffff60
	s_cmp_lt_u32 s99, 0x40
	s_cselect_b32 s14, 0x4bc, 0
	s_and_b32 s99, s82, 7
	s_add_i32 s99, s99, 0xfffffff9
	s_cmp_lt_u32 s99, 1
	s_cselect_b32 s14, s14, 0
	s_add_i32 s98, s98, s14
	s_add_i32 s99, s82, 0xffffff60
	s_cmp_lt_u32 s99, 0x20
	s_cselect_b32 s14, 0x4bf, 0
	s_and_b32 s99, s82, 7
	s_add_i32 s99, s99, 0xfffffffb
	s_cmp_lt_u32 s99, 1
	s_cselect_b32 s14, s14, 0
	s_add_i32 s98, s98, s14
	s_add_i32 s98, s98, s82
	s_ashr_i32 s3, s98, 31
	s_lshr_b32 s3, s3, 29
	s_add_i32 s3, s98, s3
	s_ashr_i32 s14, s3, 3
	s_and_b32 s3, s3, -8
	s_sub_i32 s3, s98, s3
	s_cmp_lt_i32 s3, 0
	s_cselect_b32 s15, s47, 0xb4
	s_mul_i32 s3, s15, s3
	s_add_i32 s3, s3, s14
	s_mul_hi_i32 s14, s3, 0x66666667
	s_lshr_b32 s15, s14, 31
	s_ashr_i32 s14, s14, 6
	s_add_i32 s14, s14, s15
	s_mul_i32 s15, s14, 0xa0
	s_sub_i32 s3, s3, s15
	s_bfe_u32 s15, s3, 0x3001c
	s_add_i32 s15, s3, s15
	s_sext_i32_i16 s41, s15
	s_and_b32 s15, s15, 0xfff8
	s_sub_i32 s3, s3, s15
	s_sext_i32_i16 s3, s3
	s_lshl_b32 s14, s14, 11
	s_lshl_b32 s3, s3, 8
	s_add_i32 s40, s3, s14
	s_lshl_b32 s3, s41, 5
	s_and_b32 s42, s3, 0xffffff00
